# B-out GEMM: 256 units of 272 rows, one per workgroup; the 16-row slab rides in the tile K loop (slab A fragments via small LDS-DMA slots, 8 extra MFMAs per K-step); no tail round
# speedup vs baseline: 1.0260x; 1.0260x over previous
.LBB0_1053:
	s_or_b64 exec, exec, s[38:39]
	v_readlane_b32 s0, v255, 1
	s_mov_b64 s[6:7], s[96:97]
	v_mov_b32_e32 v8, v201
	v_readlane_b32 s1, v255, 2
	s_waitcnt lgkmcnt(0)
	s_barrier
	s_and_b64 vcc, exec, s[0:1]
	v_readfirstlane_b32 s5, v8
	s_cbranch_vccnz .LBB0_1069
	v_lshlrev_b32_e32 v0, 4, v8
	v_add_u32_e32 v1, 0x2000, v0
	v_ashrrev_i32_e32 v2, 31, v1
	v_lshrrev_b32_e32 v2, 22, v2
	v_add_u32_e32 v2, v1, v2
	v_ashrrev_i32_e32 v9, 10, v2
	v_mul_i32_i24_e32 v3, 0x400, v9
	v_sub_u32_e32 v1, v1, v3
	v_lshrrev_b32_e32 v3, 4, v1
	s_load_dwordx4 s[8:11], s[6:7], 0xb8
	v_bitop3_b32 v1, v3, v1, 32 bitop3:0x6c
	v_ashrrev_i32_e32 v3, 31, v1
	v_lshrrev_b32_e32 v3, 26, v3
	v_add_u32_e32 v3, v1, v3
	v_ashrrev_i32_e32 v10, 6, v3
	v_and_b32_e32 v3, 0xc0, v3
	s_waitcnt lgkmcnt(0)
	s_add_u32 s0, s10, 0x32752000
	v_sub_u32_e32 v1, v1, v3
	v_mov_b32_e32 v3, 1
	s_addc_u32 s1, s11, 0
	v_lshlrev_b32_e32 v2, 5, v9
	v_ashrrev_i16_sdwa v1, v3, sext(v1) dst_sel:DWORD dst_unused:UNUSED_PAD src0_sel:DWORD src1_sel:BYTE_0
	s_add_u32 s34, s10, 0x3600000
	v_and_b32_e32 v2, 32, v2
	v_bfe_i32 v11, v1, 0, 16
	s_addc_u32 s35, s11, 0
	v_add_u32_e32 v1, v2, v11
	v_lshlrev_b32_e32 v2, 3, v9
	s_lshr_b32 s4, s3, 29
	v_and_b32_e32 v2, 0xffff0, v2
	s_add_i32 s4, s2, s4
	s_ashr_i32 s12, s5, 6
	v_add_lshl_u32 v2, v10, v2, 12
	s_ashr_i32 s6, s4, 3
	s_and_b32 s4, s4, -8
	s_ashr_i32 s14, s5, 8
	s_lshl_b32 s36, s12, 10
	v_lshl_add_u32 v128, v1, 1, v2
	v_bfe_i32 v2, v8, 27, 1
	s_sub_i32 s4, s2, s4
	v_lshrrev_b32_e32 v2, 22, v2
	s_cmp_lt_i32 s4, 0
	v_add_u32_e32 v2, v0, v2
	s_cselect_b32 s7, 35, 34
	v_and_b32_e32 v2, 0xfffffc00, v2
	s_mul_i32 s4, s4, s7
	v_sub_u32_e32 v0, v0, v2
	s_add_i32 s4, s4, s6
	v_lshrrev_b32_e32 v2, 4, v0
	s_ashr_i32 s6, s4, 31
	v_bitop3_b32 v2, v2, v0, 32 bitop3:0x6c
	v_ashrrev_i32_e32 v0, 31, v0
	s_lshr_b32 s6, s6, 27
	v_lshrrev_b32_e32 v0, 26, v0
	s_add_i32 s6, s4, s6
	v_ashrrev_i32_e32 v1, 31, v8
	v_add_u32_e32 v0, v2, v0
	s_ashr_i32 s7, s6, 5
	v_lshrrev_b32_e32 v1, 26, v1
	v_ashrrev_i32_e32 v13, 6, v0
	s_lshl_b32 s13, s7, 3
	v_add_u32_e32 v1, v8, v1
	v_mul_i32_i24_e32 v0, 64, v13
	s_sub_i32 s7, 0x44, s13
	v_ashrrev_i32_e32 v12, 6, v1
	v_sub_u32_e32 v0, v2, v0
	s_min_u32 s15, s7, 8
	s_andn2_b32 s6, s6, 31
	v_lshlrev_b32_e32 v1, 5, v12
	v_ashrrev_i16_sdwa v0, v3, sext(v0) dst_sel:DWORD dst_unused:UNUSED_PAD src0_sel:DWORD src1_sel:BYTE_0
	s_sub_i32 s16, s4, s6
	v_cvt_f32_ubyte0_e32 v3, s15
	v_and_b32_e32 v1, 32, v1
	v_bfe_i32 v14, v0, 0, 16
	v_cvt_f32_i32_e32 v2, s16
	v_rcp_iflag_f32_e32 v4, v3
	v_add_u32_e32 v0, v1, v14
	v_lshlrev_b32_e32 v1, 3, v12
	v_and_b32_e32 v1, 0xffff0, v1
	v_add_lshl_u32 v1, v13, v1, 12
	v_lshl_add_u32 v130, v0, 1, v1
	v_mul_f32_e32 v0, v2, v4
	v_trunc_f32_e32 v0, v0
	v_fma_f32 v1, -v0, v3, v2
	v_cvt_i32_f32_e32 v0, v0
	s_ashr_i32 s4, s16, 30
	s_or_b32 s4, s4, 1
	v_cmp_ge_f32_e64 s[6:7], |v1|, v3
	s_and_b64 s[6:7], s[6:7], exec
	s_cselect_b32 s4, s4, 0
	v_readfirstlane_b32 s6, v0
	s_add_i32 s4, s6, s4
	s_mul_i32 s6, s4, s15
	s_sub_i32 s6, s16, s6
	s_sext_i32_i8 s6, s6
	s_add_i32 s24, s13, s6
	s_and_b32 s24, s2, 7
	s_lshr_b32 s4, s2, 3
	s_lshl_b32 s24, s24, 3
	s_lshr_b32 s6, s4, 2
	s_add_i32 s24, s24, s6
	s_and_b32 s4, s4, 3
	s_ashr_i32 s25, s24, 31
	s_bfe_i64 s[16:17], s[4:5], 0x80000
	s_mul_i32 s6, s24, 0x110000
	s_mov_b32 s7, 0
	s_lshl_b64 s[16:17], s[16:17], 20
	s_add_u32 s26, s34, s16
	s_addc_u32 s27, s35, s17
	s_add_u32 s64, s0, s6
	s_addc_u32 s65, s1, s7
	s_add_u32 s64, s64, 0x100000
	s_addc_u32 s65, s65, 0
	v_lshrrev_b32_e32 v209, 6, v201
	s_nop 0
	v_readfirstlane_b32 s63, v209
	s_lshl_b32 s66, s63, 8
	s_add_i32 s66, s66, 0x20000
	v_and_b32_e32 v254, 15, v200
	v_lshlrev_b32_e32 v254, 12, v254
	v_lshl_add_u32 v254, s63, 4, v254
	v_lshlrev_b32_e32 v209, 4, v200
	v_add_u32_e32 v209, 0x20000, v209
	v_mov_b32_e32 v230, 0
	v_mov_b32_e32 v231, 0
	v_mov_b32_e32 v232, 0
	v_mov_b32_e32 v233, 0
	v_mov_b32_e32 v234, 0
	v_mov_b32_e32 v235, 0
	v_mov_b32_e32 v236, 0
	v_mov_b32_e32 v237, 0
	v_mov_b32_e32 v238, 0
	v_mov_b32_e32 v239, 0
	v_mov_b32_e32 v240, 0
	v_mov_b32_e32 v241, 0
	v_mov_b32_e32 v242, 0
	v_mov_b32_e32 v243, 0
	v_mov_b32_e32 v244, 0
	v_mov_b32_e32 v245, 0
	s_mov_b32 exec_lo, 0xffff
	s_mov_b32 exec_hi, 0
	s_mov_b32 m0, s66
	s_nop 0
	global_load_lds_dwordx4 v254, s[64:65]
	s_mov_b64 exec, -1
	s_add_i32 s25, s36, 0
	s_add_i32 m0, s25, 0x10000
	v_mov_b32_e32 v131, 0
	global_load_lds_dwordx4 v130, s[26:27]
	s_add_i32 m0, s25, 0x12000
	s_add_u32 s16, s26, 0x80000
	global_load_lds_dwordx4 v128, s[26:27]
	s_addc_u32 s17, s27, 0
	s_add_i32 m0, s25, 0x14000
	v_mov_b32_e32 v129, v131
	global_load_lds_dwordx4 v130, s[16:17]
	s_add_i32 m0, s25, 0x16000
	s_add_u32 s28, s0, s6
	s_addc_u32 s29, s1, s7
	s_add_i32 s37, s25, 0x2000
	global_load_lds_dwordx4 v128, s[16:17]
	s_mov_b32 m0, s25
	s_add_u32 s6, s28, 0x80000
	global_load_lds_dwordx4 v130, s[28:29]
	s_mov_b32 m0, s37
	s_addc_u32 s7, s29, 0
	s_add_i32 s38, s25, 0x4000
	global_load_lds_dwordx4 v128, s[28:29]
	s_mov_b32 m0, s38
	s_add_i32 s39, s25, 0x6000
	global_load_lds_dwordx4 v130, s[6:7]
	s_mov_b32 m0, s39
	s_cmp_eq_u32 s14, 1
	global_load_lds_dwordx4 v128, s[6:7]
	s_mov_b32 s40, 0
	v_lshl_add_u64 v[6:7], s[26:27], 0, v[130:131]
	v_lshl_add_u64 v[4:5], s[26:27], 0, v[128:129]
	v_lshl_add_u64 v[0:1], s[28:29], 0, v[130:131]
	s_cselect_b64 s[6:7], -1, 0
	s_cmp_lg_u32 s14, 1
	v_lshl_add_u64 v[2:3], s[28:29], 0, v[128:129]
	s_cbranch_scc1 .LBB0_1056
	s_barrier
.LBB0_1056:
	s_add_u32 s10, s10, 0x36b52000
	s_addc_u32 s11, s11, 0
	s_lshl_b32 s12, s12, 5
	s_and_b32 s18, s12, 0x60
	s_mov_b64 s[12:13], 0x80
	s_add_i32 m0, s25, 0x18000
	v_lshl_add_u64 v[6:7], v[6:7], 0, s[12:13]
	s_lshl_b32 s15, s14, 13
	s_lshl_b32 s19, s18, 7
	s_waitcnt vmcnt(2)
	s_barrier
	s_add_u32 s60, s64, 0x80
	s_addc_u32 s61, s65, 0
	s_mov_b32 exec_lo, 0xffff
	s_mov_b32 exec_hi, 0
	s_add_i32 m0, s66, 0x800
	s_nop 0
	global_load_lds_dwordx4 v254, s[60:61]
	s_mov_b64 exec, -1
	s_add_i32 m0, s25, 0x18000
	s_nop 0
	global_load_lds_dwordx4 v[6:7], off
	v_lshl_add_u64 v[4:5], v[4:5], 0, s[12:13]
	s_add_i32 m0, s25, 0x1a000
	s_add_i32 s41, s25, 0x8000
	s_add_i32 s42, s25, 0xa000
	global_load_lds_dwordx4 v[4:5], off
	v_lshl_add_u64 v[0:1], v[0:1], 0, s[12:13]
	s_mov_b32 m0, s41
	s_add_u32 s16, s26, 0x80080
	global_load_lds_dwordx4 v[0:1], off
	v_lshl_add_u64 v[0:1], v[2:3], 0, s[12:13]
	s_mov_b32 m0, s42
	s_addc_u32 s17, s27, 0
	global_load_lds_dwordx4 v[0:1], off
	s_add_i32 m0, s25, 0x1c000
	v_lshl_add_u64 v[0:1], s[16:17], 0, v[130:131]
	global_load_lds_dwordx4 v[0:1], off
	v_lshl_add_u64 v[0:1], s[16:17], 0, v[128:129]
	s_add_i32 m0, s25, 0x1e000
	s_cmpk_lt_u32 s5, 0x100
	global_load_lds_dwordx4 v[0:1], off
	v_bfe_u32 v1, v8, 4, 2
	v_and_b32_e32 v0, 15, v8
	v_lshlrev_b32_e32 v2, 4, v1
	v_lshl_or_b32 v144, s14, 6, v0
	v_lshl_or_b32 v0, v0, 6, v2
	v_lshlrev_b32_e32 v2, 2, v8
	v_and_b32_e32 v2, 32, v2
	v_bitop3_b32 v3, v0, s15, v2 bitop3:0xde
	v_bitop3_b32 v145, v0, s19, v2 bitop3:0xde
	v_lshlrev_b32_e32 v0, 15, v9
	v_and_b32_e32 v0, 0xffff0000, v0
	v_lshl_or_b32 v146, v1, 2, s18
	v_lshl_add_u32 v0, v10, 12, v0
	v_and_b32_e32 v1, 1, v9
	v_lshl_or_b32 v0, v1, 6, v0
	v_lshl_add_u32 v132, v11, 1, v0
	v_lshlrev_b32_e32 v0, 15, v12
	v_and_b32_e32 v0, 0xffff0000, v0
	s_waitcnt vmcnt(6)
	v_lshl_add_u32 v0, v13, 12, v0
	v_and_b32_e32 v1, 1, v12
	s_cselect_b64 s[14:15], -1, 0
	v_lshl_or_b32 v0, v1, 6, v0
	s_add_i32 s43, 0, 0x10000
	s_add_i32 s44, 0, 0x14000
	s_sext_i32_i8 s46, s4
	v_mov_b32_e32 v133, v131
	v_lshl_add_u32 v134, v14, 1, v0
	v_mov_b32_e32 v135, v131
	v_mov_b64_e32 v[136:137], 0
	v_mov_b64_e32 v[138:139], 0
	v_add_u32_e32 v147, s43, v145
	v_add_u32_e32 v148, s44, v145
	v_add_u32_e32 v149, 0, v3
	s_movk_i32 s45, 0x4400
	s_barrier
	s_branch .LBB0_1059

.LBB0_1062:
	ds_read_b128 v[140:143], v147
	ds_read_b128 v[150:153], v147 offset:1024
	ds_read_b128 v[154:157], v147 offset:2048
	ds_read_b128 v[158:161], v147 offset:3072
	ds_read_b128 v[162:165], v148
	ds_read_b128 v[166:169], v148 offset:1024
	ds_read_b128 v[170:173], v148 offset:2048
	ds_read_b128 v[174:177], v148 offset:3072
	s_add_u32 s28, s26, 0xfff80080
	s_addc_u32 s29, s27, -1
	s_cmp_eq_u32 s51, 28
	s_cselect_b32 s31, s19, s29
	s_cselect_b32 s30, s47, s28
	s_cselect_b32 s29, s17, s50
	s_cselect_b32 s28, s48, s49
	v_lshl_add_u64 v[198:199], s[26:27], 0, v[134:135]
	s_add_i32 m0, s25, 0xc000
	ds_read_b128 v[178:181], v149
	ds_read_b128 v[182:185], v149 offset:1024
	ds_read_b128 v[186:189], v149 offset:2048
	ds_read_b128 v[190:193], v149 offset:3072
	ds_read_b128 v[194:197], v149 offset:4096
	ds_read_b128 v[210:213], v149 offset:5120
	ds_read_b128 v[214:217], v149 offset:6144
	ds_read_b128 v[218:221], v149 offset:7168
	ds_read_b128 v[246:249], v209
	ds_read_b128 v[250:253], v209 offset:1024
	global_load_lds_dwordx4 v[198:199], off
	v_lshl_add_u64 v[198:199], s[26:27], 0, v[132:133]
	s_add_i32 m0, s25, 0xe000
	s_nop 0
	global_load_lds_dwordx4 v[198:199], off
	s_waitcnt vmcnt(9)
	s_waitcnt lgkmcnt(0)
	s_barrier
	s_setprio 1
	s_waitcnt lgkmcnt(0)
	v_mfma_f32_16x16x32_bf16 v[124:127], v[140:143], v[178:181], v[124:127]
	v_mfma_f32_16x16x32_bf16 v[120:123], v[154:157], v[178:181], v[120:123]
	v_mfma_f32_16x16x32_bf16 v[112:115], v[140:143], v[186:189], v[112:115]
	v_mfma_f32_16x16x32_bf16 v[104:107], v[154:157], v[186:189], v[104:107]
	v_mfma_f32_16x16x32_bf16 v[96:99], v[140:143], v[194:197], v[96:99]
	v_mfma_f32_16x16x32_bf16 v[88:91], v[154:157], v[194:197], v[88:91]
	v_mfma_f32_16x16x32_bf16 v[80:83], v[140:143], v[214:217], v[80:83]
	v_mfma_f32_16x16x32_bf16 v[72:75], v[154:157], v[214:217], v[72:75]
	v_mfma_f32_16x16x32_bf16 v[124:127], v[150:153], v[182:185], v[124:127]
	v_mfma_f32_16x16x32_bf16 v[120:123], v[158:161], v[182:185], v[120:123]
	v_mfma_f32_16x16x32_bf16 v[112:115], v[150:153], v[190:193], v[112:115]
	v_mfma_f32_16x16x32_bf16 v[104:107], v[158:161], v[190:193], v[104:107]
	v_mfma_f32_16x16x32_bf16 v[96:99], v[150:153], v[210:213], v[96:99]
	v_mfma_f32_16x16x32_bf16 v[88:91], v[158:161], v[210:213], v[88:91]
	v_mfma_f32_16x16x32_bf16 v[80:83], v[150:153], v[218:221], v[80:83]
	v_mfma_f32_16x16x32_bf16 v[72:75], v[158:161], v[218:221], v[72:75]
	v_mfma_f32_16x16x32_bf16 v[230:233], v[140:143], v[246:249], v[230:233]
	v_mfma_f32_16x16x32_bf16 v[234:237], v[154:157], v[246:249], v[234:237]
	v_mfma_f32_16x16x32_bf16 v[230:233], v[150:153], v[250:253], v[230:233]
	v_mfma_f32_16x16x32_bf16 v[234:237], v[158:161], v[250:253], v[234:237]
	s_setprio 0
	s_setprio 1
	v_mfma_f32_16x16x32_bf16 v[116:119], v[162:165], v[178:181], v[116:119]
	v_mfma_f32_16x16x32_bf16 v[108:111], v[170:173], v[178:181], v[108:111]
	v_mfma_f32_16x16x32_bf16 v[100:103], v[162:165], v[186:189], v[100:103]
	v_mfma_f32_16x16x32_bf16 v[92:95], v[170:173], v[186:189], v[92:95]
	v_mfma_f32_16x16x32_bf16 v[84:87], v[162:165], v[194:197], v[84:87]
	v_mfma_f32_16x16x32_bf16 v[76:79], v[170:173], v[194:197], v[76:79]
	v_mfma_f32_16x16x32_bf16 v[68:71], v[162:165], v[214:217], v[68:71]
	v_mfma_f32_16x16x32_bf16 v[64:67], v[170:173], v[214:217], v[64:67]
	v_mfma_f32_16x16x32_bf16 v[116:119], v[166:169], v[182:185], v[116:119]
	v_mfma_f32_16x16x32_bf16 v[108:111], v[174:177], v[182:185], v[108:111]
	v_mfma_f32_16x16x32_bf16 v[100:103], v[166:169], v[190:193], v[100:103]
	v_mfma_f32_16x16x32_bf16 v[92:95], v[174:177], v[190:193], v[92:95]
	v_mfma_f32_16x16x32_bf16 v[84:87], v[166:169], v[210:213], v[84:87]
	v_mfma_f32_16x16x32_bf16 v[76:79], v[174:177], v[210:213], v[76:79]
	v_mfma_f32_16x16x32_bf16 v[68:71], v[166:169], v[218:221], v[68:71]
	v_mfma_f32_16x16x32_bf16 v[64:67], v[174:177], v[218:221], v[64:67]
	v_mfma_f32_16x16x32_bf16 v[238:241], v[162:165], v[246:249], v[238:241]
	v_mfma_f32_16x16x32_bf16 v[242:245], v[170:173], v[246:249], v[242:245]
	v_mfma_f32_16x16x32_bf16 v[238:241], v[166:169], v[250:253], v[238:241]
	v_mfma_f32_16x16x32_bf16 v[242:245], v[174:177], v[250:253], v[242:245]
	s_setprio 0
	s_barrier
	s_add_u32 s60, s26, 0x80080
	s_addc_u32 s61, s27, 0
	s_mov_b32 exec_lo, 0xffff
	s_mov_b32 exec_hi, 0
	s_mov_b32 m0, s66
	s_nop 0
	global_load_lds_dwordx4 v254, s[60:61]
	s_mov_b64 exec, -1
	s_add_i32 s54, s43, s36
	v_lshl_add_u64 v[198:199], s[28:29], 0, v[130:131]
	s_mov_b32 m0, s54
	ds_read_b128 v[178:181], v149 offset:16384
	ds_read_b128 v[182:185], v149 offset:17408
	ds_read_b128 v[186:189], v149 offset:18432
	ds_read_b128 v[190:193], v149 offset:19456
	ds_read_b128 v[194:197], v149 offset:20480
	ds_read_b128 v[210:213], v149 offset:21504
	ds_read_b128 v[214:217], v149 offset:22528
	ds_read_b128 v[218:221], v149 offset:23552
	global_load_lds_dwordx4 v[198:199], off
	s_add_i32 m0, s54, 0x2000
	s_add_u32 s54, s28, 0x80000
	v_lshl_add_u64 v[222:223], s[28:29], 0, v[128:129]
	s_addc_u32 s55, s29, 0
	s_add_i32 s56, s44, s36
	global_load_lds_dwordx4 v[222:223], off
	v_lshl_add_u64 v[224:225], s[54:55], 0, v[130:131]
	s_mov_b32 m0, s56
	v_lshl_add_u64 v[226:227], s[30:31], 0, v[128:129]
	global_load_lds_dwordx4 v[224:225], off
	v_lshl_add_u64 v[224:225], s[54:55], 0, v[128:129]
	s_add_i32 m0, s56, 0x2000
	s_nop 0
	global_load_lds_dwordx4 v[224:225], off
	v_lshl_add_u64 v[224:225], s[30:31], 0, v[130:131]
	s_mov_b32 m0, s25
	s_nop 0
	global_load_lds_dwordx4 v[224:225], off
	s_mov_b32 m0, s37
	s_nop 0
	global_load_lds_dwordx4 v[226:227], off
	s_waitcnt vmcnt(9)
	s_waitcnt lgkmcnt(0)
	s_barrier
	s_setprio 1
	s_waitcnt lgkmcnt(0)
	v_mfma_f32_16x16x32_bf16 v[60:63], v[140:143], v[178:181], v[60:63]
	v_mfma_f32_16x16x32_bf16 v[56:59], v[154:157], v[178:181], v[56:59]
	v_mfma_f32_16x16x32_bf16 v[48:51], v[140:143], v[186:189], v[48:51]
	v_mfma_f32_16x16x32_bf16 v[40:43], v[154:157], v[186:189], v[40:43]
	v_mfma_f32_16x16x32_bf16 v[32:35], v[140:143], v[194:197], v[32:35]
	v_mfma_f32_16x16x32_bf16 v[24:27], v[154:157], v[194:197], v[24:27]
	v_mfma_f32_16x16x32_bf16 v[16:19], v[140:143], v[214:217], v[16:19]
	v_mfma_f32_16x16x32_bf16 v[8:11], v[154:157], v[214:217], v[8:11]
	v_mfma_f32_16x16x32_bf16 v[60:63], v[150:153], v[182:185], v[60:63]
	v_mfma_f32_16x16x32_bf16 v[56:59], v[158:161], v[182:185], v[56:59]
	v_mfma_f32_16x16x32_bf16 v[48:51], v[150:153], v[190:193], v[48:51]
	v_mfma_f32_16x16x32_bf16 v[40:43], v[158:161], v[190:193], v[40:43]
	v_mfma_f32_16x16x32_bf16 v[32:35], v[150:153], v[210:213], v[32:35]
	v_mfma_f32_16x16x32_bf16 v[24:27], v[158:161], v[210:213], v[24:27]
	v_mfma_f32_16x16x32_bf16 v[16:19], v[150:153], v[218:221], v[16:19]
	v_mfma_f32_16x16x32_bf16 v[8:11], v[158:161], v[218:221], v[8:11]
	s_setprio 0
	s_setprio 1
	v_mfma_f32_16x16x32_bf16 v[52:55], v[162:165], v[178:181], v[52:55]
	v_mfma_f32_16x16x32_bf16 v[44:47], v[170:173], v[178:181], v[44:47]
	v_mfma_f32_16x16x32_bf16 v[36:39], v[162:165], v[186:189], v[36:39]
	v_mfma_f32_16x16x32_bf16 v[28:31], v[170:173], v[186:189], v[28:31]
	v_mfma_f32_16x16x32_bf16 v[20:23], v[162:165], v[194:197], v[20:23]
	v_mfma_f32_16x16x32_bf16 v[12:15], v[170:173], v[194:197], v[12:15]
	v_mfma_f32_16x16x32_bf16 v[4:7], v[162:165], v[214:217], v[4:7]
	v_mfma_f32_16x16x32_bf16 v[0:3], v[170:173], v[214:217], v[0:3]
	v_mfma_f32_16x16x32_bf16 v[52:55], v[166:169], v[182:185], v[52:55]
	v_mfma_f32_16x16x32_bf16 v[44:47], v[174:177], v[182:185], v[44:47]
	v_mfma_f32_16x16x32_bf16 v[36:39], v[166:169], v[190:193], v[36:39]
	v_mfma_f32_16x16x32_bf16 v[28:31], v[174:177], v[190:193], v[28:31]
	v_mfma_f32_16x16x32_bf16 v[20:23], v[166:169], v[210:213], v[20:23]
	v_mfma_f32_16x16x32_bf16 v[12:15], v[174:177], v[210:213], v[12:15]
	v_mfma_f32_16x16x32_bf16 v[4:7], v[166:169], v[218:221], v[4:7]
	v_mfma_f32_16x16x32_bf16 v[0:3], v[174:177], v[218:221], v[0:3]
	s_setprio 0
	s_barrier
	s_add_i32 s54, 0, 0x18000
	s_add_i32 s55, 0, 0x1c000
	v_add_u32_e32 v158, s54, v145
	v_add_u32_e32 v174, s55, v145
	ds_read_b128 v[140:143], v158
	ds_read_b128 v[150:153], v158 offset:1024
	ds_read_b128 v[154:157], v158 offset:2048
	ds_read_b128 v[158:161], v158 offset:3072
	ds_read_b128 v[162:165], v174
	ds_read_b128 v[166:169], v174 offset:1024
	ds_read_b128 v[170:173], v174 offset:2048
	ds_read_b128 v[174:177], v174 offset:3072
	s_add_u32 s30, s30, 0x80000
	s_addc_u32 s31, s31, 0
	s_mov_b32 m0, s38
	v_lshl_add_u64 v[228:229], s[30:31], 0, v[130:131]
	ds_read_b128 v[178:181], v149 offset:32768
	ds_read_b128 v[182:185], v149 offset:33792
	ds_read_b128 v[186:189], v149 offset:34816
	ds_read_b128 v[190:193], v149 offset:35840
	ds_read_b128 v[194:197], v149 offset:36864
	ds_read_b128 v[210:213], v149 offset:37888
	ds_read_b128 v[214:217], v149 offset:38912
	ds_read_b128 v[218:221], v149 offset:39936
	ds_read_b128 v[246:249], v209 offset:2048
	ds_read_b128 v[250:253], v209 offset:3072
	global_load_lds_dwordx4 v[228:229], off
	v_lshl_add_u64 v[228:229], s[30:31], 0, v[128:129]
	s_mov_b32 m0, s39
	s_nop 0
	global_load_lds_dwordx4 v[228:229], off
	s_waitcnt vmcnt(9)
	s_waitcnt lgkmcnt(0)
	s_barrier
	s_setprio 1
	s_waitcnt lgkmcnt(0)
	v_mfma_f32_16x16x32_bf16 v[124:127], v[140:143], v[178:181], v[124:127]
	v_mfma_f32_16x16x32_bf16 v[120:123], v[154:157], v[178:181], v[120:123]
	v_mfma_f32_16x16x32_bf16 v[112:115], v[140:143], v[186:189], v[112:115]
	v_mfma_f32_16x16x32_bf16 v[104:107], v[154:157], v[186:189], v[104:107]
	v_mfma_f32_16x16x32_bf16 v[96:99], v[140:143], v[194:197], v[96:99]
	v_mfma_f32_16x16x32_bf16 v[88:91], v[154:157], v[194:197], v[88:91]
	v_mfma_f32_16x16x32_bf16 v[80:83], v[140:143], v[214:217], v[80:83]
	v_mfma_f32_16x16x32_bf16 v[72:75], v[154:157], v[214:217], v[72:75]
	v_mfma_f32_16x16x32_bf16 v[124:127], v[150:153], v[182:185], v[124:127]
	v_mfma_f32_16x16x32_bf16 v[120:123], v[158:161], v[182:185], v[120:123]
	v_mfma_f32_16x16x32_bf16 v[112:115], v[150:153], v[190:193], v[112:115]
	v_mfma_f32_16x16x32_bf16 v[104:107], v[158:161], v[190:193], v[104:107]
	v_mfma_f32_16x16x32_bf16 v[96:99], v[150:153], v[210:213], v[96:99]
	v_mfma_f32_16x16x32_bf16 v[88:91], v[158:161], v[210:213], v[88:91]
	v_mfma_f32_16x16x32_bf16 v[80:83], v[150:153], v[218:221], v[80:83]
	v_mfma_f32_16x16x32_bf16 v[72:75], v[158:161], v[218:221], v[72:75]
	v_mfma_f32_16x16x32_bf16 v[230:233], v[140:143], v[246:249], v[230:233]
	v_mfma_f32_16x16x32_bf16 v[234:237], v[154:157], v[246:249], v[234:237]
	v_mfma_f32_16x16x32_bf16 v[230:233], v[150:153], v[250:253], v[230:233]
	v_mfma_f32_16x16x32_bf16 v[234:237], v[158:161], v[250:253], v[234:237]
	s_setprio 0
	s_setprio 1
	v_mfma_f32_16x16x32_bf16 v[116:119], v[162:165], v[178:181], v[116:119]
	v_mfma_f32_16x16x32_bf16 v[108:111], v[170:173], v[178:181], v[108:111]
	v_mfma_f32_16x16x32_bf16 v[100:103], v[162:165], v[186:189], v[100:103]
	v_mfma_f32_16x16x32_bf16 v[92:95], v[170:173], v[186:189], v[92:95]
	v_mfma_f32_16x16x32_bf16 v[84:87], v[162:165], v[194:197], v[84:87]
	v_mfma_f32_16x16x32_bf16 v[76:79], v[170:173], v[194:197], v[76:79]
	v_mfma_f32_16x16x32_bf16 v[68:71], v[162:165], v[214:217], v[68:71]
	v_mfma_f32_16x16x32_bf16 v[64:67], v[170:173], v[214:217], v[64:67]
	v_mfma_f32_16x16x32_bf16 v[116:119], v[166:169], v[182:185], v[116:119]
	v_mfma_f32_16x16x32_bf16 v[108:111], v[174:177], v[182:185], v[108:111]
	v_mfma_f32_16x16x32_bf16 v[100:103], v[166:169], v[190:193], v[100:103]
	v_mfma_f32_16x16x32_bf16 v[92:95], v[174:177], v[190:193], v[92:95]
	v_mfma_f32_16x16x32_bf16 v[84:87], v[166:169], v[210:213], v[84:87]
	v_mfma_f32_16x16x32_bf16 v[76:79], v[174:177], v[210:213], v[76:79]
	v_mfma_f32_16x16x32_bf16 v[68:71], v[166:169], v[218:221], v[68:71]
	v_mfma_f32_16x16x32_bf16 v[64:67], v[174:177], v[218:221], v[64:67]
	v_mfma_f32_16x16x32_bf16 v[238:241], v[162:165], v[246:249], v[238:241]
	v_mfma_f32_16x16x32_bf16 v[242:245], v[170:173], v[246:249], v[242:245]
	v_mfma_f32_16x16x32_bf16 v[238:241], v[166:169], v[250:253], v[238:241]
	v_mfma_f32_16x16x32_bf16 v[242:245], v[174:177], v[250:253], v[242:245]
	s_setprio 0
	s_barrier
	s_add_u32 s60, s26, 0x80100
	s_addc_u32 s61, s27, 0
	s_mov_b32 exec_lo, 0xffff
	s_mov_b32 exec_hi, 0
	s_add_i32 m0, s66, 0x800
	s_nop 0
	global_load_lds_dwordx4 v254, s[60:61]
	s_mov_b64 exec, -1
	s_add_i32 s30, s54, s36
	v_lshl_add_u64 v[198:199], v[198:199], 0, s[12:13]
	s_mov_b32 m0, s30
	ds_read_b128 v[178:181], v149 offset:49152
	ds_read_b128 v[182:185], v149 offset:50176
	ds_read_b128 v[186:189], v149 offset:51200
	ds_read_b128 v[190:193], v149 offset:52224
	ds_read_b128 v[194:197], v149 offset:53248
	ds_read_b128 v[210:213], v149 offset:54272
	ds_read_b128 v[214:217], v149 offset:55296
	ds_read_b128 v[218:221], v149 offset:56320
	global_load_lds_dwordx4 v[198:199], off
	s_add_i32 m0, s30, 0x2000
	s_add_u32 s28, s28, 0x80080
	v_lshl_add_u64 v[198:199], v[222:223], 0, s[12:13]
	s_addc_u32 s29, s29, 0
	s_add_i32 s30, s55, s36
	global_load_lds_dwordx4 v[198:199], off
	v_lshl_add_u64 v[198:199], s[28:29], 0, v[130:131]
	s_mov_b32 m0, s30
	s_nop 0
	global_load_lds_dwordx4 v[198:199], off
	v_lshl_add_u64 v[198:199], s[28:29], 0, v[128:129]
	s_add_i32 m0, s30, 0x2000
	s_nop 0
	global_load_lds_dwordx4 v[198:199], off
	v_lshl_add_u64 v[198:199], v[224:225], 0, s[12:13]
	s_mov_b32 m0, s41
	s_nop 0
	global_load_lds_dwordx4 v[198:199], off
	v_lshl_add_u64 v[198:199], v[226:227], 0, s[12:13]
	s_mov_b32 m0, s42
	s_nop 0
	global_load_lds_dwordx4 v[198:199], off
	s_waitcnt vmcnt(9)
	s_waitcnt lgkmcnt(0)
	s_barrier
	s_setprio 1
	s_waitcnt lgkmcnt(0)
	v_mfma_f32_16x16x32_bf16 v[60:63], v[140:143], v[178:181], v[60:63]
	v_mfma_f32_16x16x32_bf16 v[56:59], v[154:157], v[178:181], v[56:59]
	v_mfma_f32_16x16x32_bf16 v[48:51], v[140:143], v[186:189], v[48:51]
	v_mfma_f32_16x16x32_bf16 v[40:43], v[154:157], v[186:189], v[40:43]
	v_mfma_f32_16x16x32_bf16 v[32:35], v[140:143], v[194:197], v[32:35]
	v_mfma_f32_16x16x32_bf16 v[24:27], v[154:157], v[194:197], v[24:27]
	v_mfma_f32_16x16x32_bf16 v[16:19], v[140:143], v[214:217], v[16:19]
	v_mfma_f32_16x16x32_bf16 v[8:11], v[154:157], v[214:217], v[8:11]
	v_mfma_f32_16x16x32_bf16 v[60:63], v[150:153], v[182:185], v[60:63]
	v_mfma_f32_16x16x32_bf16 v[56:59], v[158:161], v[182:185], v[56:59]
	v_mfma_f32_16x16x32_bf16 v[48:51], v[150:153], v[190:193], v[48:51]
	v_mfma_f32_16x16x32_bf16 v[40:43], v[158:161], v[190:193], v[40:43]
	v_mfma_f32_16x16x32_bf16 v[32:35], v[150:153], v[210:213], v[32:35]
	v_mfma_f32_16x16x32_bf16 v[24:27], v[158:161], v[210:213], v[24:27]
	v_mfma_f32_16x16x32_bf16 v[16:19], v[150:153], v[218:221], v[16:19]
	v_mfma_f32_16x16x32_bf16 v[8:11], v[158:161], v[218:221], v[8:11]
	s_setprio 0
	s_setprio 1
	v_mfma_f32_16x16x32_bf16 v[52:55], v[162:165], v[178:181], v[52:55]
	v_mfma_f32_16x16x32_bf16 v[44:47], v[170:173], v[178:181], v[44:47]
	v_mfma_f32_16x16x32_bf16 v[36:39], v[162:165], v[186:189], v[36:39]
	v_mfma_f32_16x16x32_bf16 v[28:31], v[170:173], v[186:189], v[28:31]
	v_mfma_f32_16x16x32_bf16 v[20:23], v[162:165], v[194:197], v[20:23]
	v_mfma_f32_16x16x32_bf16 v[12:15], v[170:173], v[194:197], v[12:15]
	v_mfma_f32_16x16x32_bf16 v[4:7], v[162:165], v[214:217], v[4:7]
	v_mfma_f32_16x16x32_bf16 v[0:3], v[170:173], v[214:217], v[0:3]
	v_mfma_f32_16x16x32_bf16 v[52:55], v[166:169], v[182:185], v[52:55]
	v_mfma_f32_16x16x32_bf16 v[44:47], v[174:177], v[182:185], v[44:47]
	v_mfma_f32_16x16x32_bf16 v[36:39], v[166:169], v[190:193], v[36:39]
	v_mfma_f32_16x16x32_bf16 v[28:31], v[174:177], v[190:193], v[28:31]
	v_mfma_f32_16x16x32_bf16 v[20:23], v[166:169], v[210:213], v[20:23]
	v_mfma_f32_16x16x32_bf16 v[12:15], v[174:177], v[210:213], v[12:15]
	v_mfma_f32_16x16x32_bf16 v[4:7], v[166:169], v[218:221], v[4:7]
	v_mfma_f32_16x16x32_bf16 v[0:3], v[174:177], v[218:221], v[0:3]
	s_setprio 0
	s_barrier
	s_add_i32 s51, s51, 2
	s_add_u32 s49, s49, 0x100
	s_addc_u32 s50, s50, 0
	s_add_u32 s26, s26, 0x100
	s_addc_u32 s27, s27, 0
	s_cmp_gt_u32 s51, 29
	s_cbranch_scc0 .LBB0_1062
	s_and_b64 vcc, exec, s[14:15]
	s_cbranch_vccz .LBB0_1065
	s_barrier

.LBB0_1068:
	s_and_b32 s60, s2, 7
	s_lshr_b32 s61, s2, 3
	s_lshl_b32 s60, s60, 3
	s_lshr_b32 s62, s61, 2
	s_add_i32 s60, s60, s62
	s_and_b32 s61, s61, 3
	s_mul_i32 s62, s60, 0x110
	s_addk_i32 s62, 0x100
	s_lshr_b32 s67, s63, 2
	s_and_b32 s68, s63, 3
	s_lshl_b32 s69, s61, 8
	s_lshl_b32 s70, s67, 7
	s_add_i32 s69, s69, s70
	s_lshl_b32 s70, s68, 5
	s_add_i32 s69, s69, s70
	s_lshl_b32 s69, s69, 2
	s_lshl_b32 s70, s62, 12
	s_add_u32 s69, s69, s70
	s_add_u32 s70, s10, s69
	s_addc_u32 s71, s11, 0
	s_add_u32 s72, s8, s69
	s_addc_u32 s73, s9, 0
	v_and_b32_e32 v0, 15, v200
	v_lshrrev_b32_e32 v1, 4, v200
	v_lshlrev_b32_e32 v0, 12, v0
	v_lshl_add_u32 v0, v1, 4, v0
	global_load_dwordx4 v[2:5], v0, s[70:71]
	global_load_dwordx4 v[6:9], v0, s[70:71] offset:64
	s_cmp_eq_u32 s67, 0
	s_cbranch_scc1 .Lslab9_wr0
	v_mov_b32_e32 v230, v238
	v_mov_b32_e32 v231, v239
	v_mov_b32_e32 v232, v240
	v_mov_b32_e32 v233, v241
	v_mov_b32_e32 v234, v242
	v_mov_b32_e32 v235, v243
	v_mov_b32_e32 v236, v244
	v_mov_b32_e32 v237, v245
.Lslab9_wr0:
	s_waitcnt vmcnt(0)
	v_pk_add_f32 v[230:231], v[2:3], v[230:231]
	v_pk_add_f32 v[232:233], v[4:5], v[232:233]
	v_pk_add_f32 v[234:235], v[6:7], v[234:235]
	v_pk_add_f32 v[236:237], v[8:9], v[236:237]
	global_store_dwordx4 v0, v[230:233], s[72:73]
	global_store_dwordx4 v0, v[234:237], s[72:73] offset:64
	s_waitcnt vmcnt(0)
	s_barrier
